# barriers 1-5: no cross-XCD arrival counter; every XCD leader adds 1 to all 16 per-XCD generation words, workgroups wait for nx more on their own word
# speedup vs baseline: 1.0120x; 1.0028x over previous
; __device__ __forceinline__ unsigned xb_ld(unsigned* p)              { return __hip_atomic_load(p, __ATOMIC_RELAXED, __HIP_MEMORY_SCOPE_AGENT); }
; __device__ __forceinline__ unsigned xb_add(unsigned* p, unsigned v) { return __hip_atomic_fetch_add(p, v, __ATOMIC_RELAXED, __HIP_MEMORY_SCOPE_AGENT); }
; #define XB_SPIN(cond, bar) do { unsigned _sp = 0; while (cond) { __builtin_amdgcn_s_sleep(1); \
;     if ((++_sp & 255u) == 0u) { if (xb_ld(&(bar)[XB_TMO])) break; if (_sp > XB_SPIN_CAP) { atomicAdd(&(bar)[XB_TMO], 1u); break; } } } } while (0)
; __device__ __forceinline__ void xcd_barrier(const XcdBarrier& b) {
;     asm volatile("s_waitcnt vmcnt(0)" ::: "memory");
;     __syncthreads();
;     if (threadIdx.x == 0) {
;         unsigned* bar = b.bar;
;         __builtin_amdgcn_s_waitcnt(0);
;         unsigned nloc = b.st[0], nx = b.st[1];
;         if (nloc == 0u) { xcd_barrier_complete(bar, b.x, nloc, nx); b.st[0] = nloc; b.st[1] = nx; }
;         const unsigned old = xb_add(&bar[XB_XSUB(b.x)], 1u);
;         const unsigned gen = old / nloc;
;         if (old + 1u == (gen + 1u) * nloc) {
;             __builtin_amdgcn_fence(__ATOMIC_RELEASE, "agent");
;             asm volatile("s_waitcnt vmcnt(0)" ::: "memory");
;             const unsigned og = xb_add(&bar[XB_TOP], 1u);
;             const unsigned tg = og / nx;
;             if (og + 1u == (tg + 1u) * nx) xb_add(&bar[XB_TOPGEN], 1u);
;             else XB_SPIN(xb_ld(&bar[XB_TOPGEN]) == tg, bar);
;             __builtin_amdgcn_fence(__ATOMIC_ACQUIRE, "agent");
;             xb_add(&bar[XB_XGEN(b.x)], 1u);
;             asm volatile("s_waitcnt vmcnt(0)" ::: "memory");
;         } else {
;             XB_SPIN(xb_ld(&bar[XB_XGEN(b.x)]) == gen, bar);
;             __builtin_amdgcn_fence(__ATOMIC_ACQUIRE, "agent");
;             asm volatile("s_waitcnt vmcnt(0)" ::: "memory");
;         }
.LBB0_157:
	s_cmp_gt_i32 s75, 2
	s_cselect_b64 s[0:1], -1, 0
	s_and_b64 s[2:3], s[4:5], s[0:1]
	s_andn2_b64 vcc, exec, s[2:3]
	s_cbranch_vccnz .LBB0_211
	s_waitcnt vmcnt(0)
	s_waitcnt vmcnt(0) lgkmcnt(0)
	s_barrier
	s_mov_b64 s[2:3], exec
	v_readlane_b32 s4, v254, 9
	v_readlane_b32 s5, v254, 10
	s_and_b64 s[4:5], s[2:3], s[4:5]
	s_mov_b64 exec, s[4:5]
	s_cbranch_execz .LBB0_210
	s_cmp_eq_u32 s74, 1
	s_cbranch_scc1 .Lmy_fb_1_orig
	s_add_i32 s4, 0, 0x26700
	v_mov_b32_e32 v0, s4
	ds_read2_b32 v[2:3], v0 offset1:1
	s_lshl_b32 s4, s88, 8
	s_add_u32 s4, s72, s4
	s_addc_u32 s5, s73, 0
	v_mov_b32_e32 v4, 0x1000
	v_mov_b32_e32 v5, 1
	global_atomic_add v4, v4, v5, s[4:5] offset:1024 sc0
	s_sub_i32 s6, 2, s74
	s_waitcnt lgkmcnt(0)
	v_readfirstlane_b32 s7, v2
	v_readfirstlane_b32 s8, v3
	s_mul_i32 s7, s7, s6
	s_add_i32 s6, s6, -1
	s_mul_i32 s8, s8, s6
	s_add_i32 s8, s8, 1
	v_mov_b32_e32 v6, 0x2000
	s_waitcnt vmcnt(0)
	v_readfirstlane_b32 s10, v4
	s_add_i32 s10, s10, 1
	s_cmp_lg_u32 s10, s7
	s_cbranch_scc1 .Lmy_fb_1_wait
	buffer_wbl2 sc1
	s_mov_b64 s[10:11], exec
	s_mov_b64 exec, 0xffff
	v_mbcnt_lo_u32_b32 v7, -1, 0
	v_lshlrev_b32_e32 v7, 8, v7
	v_add_u32_e32 v7, 0x2400, v7
	v_mov_b32_e32 v8, 1
	s_waitcnt vmcnt(0)
	global_atomic_add v7, v8, s[72:73]
	s_mov_b64 exec, s[10:11]

; __device__ __forceinline__ unsigned xb_ld(unsigned* p)              { return __hip_atomic_load(p, __ATOMIC_RELAXED, __HIP_MEMORY_SCOPE_AGENT); }
; #define XB_SPIN(cond, bar) do { unsigned _sp = 0; while (cond) { __builtin_amdgcn_s_sleep(1); \
;     if ((++_sp & 255u) == 0u) { if (xb_ld(&(bar)[XB_TMO])) break; if (_sp > XB_SPIN_CAP) { atomicAdd(&(bar)[XB_TMO], 1u); break; } } } } while (0)
; __device__ __forceinline__ void xcd_barrier(const XcdBarrier& b) {
;     ...
;             XB_SPIN(xb_ld(&bar[XB_XGEN(b.x)]) == gen, bar);
;             __builtin_amdgcn_fence(__ATOMIC_ACQUIRE, "agent");
;             asm volatile("s_waitcnt vmcnt(0)" ::: "memory");
.Lmy_fb_1_spin:
	global_load_dword v0, v6, s[4:5] offset:1024 sc1
	s_waitcnt vmcnt(0)
	v_readfirstlane_b32 s10, v0
	s_cmp_ge_u32 s10, s8
	s_cbranch_scc1 .LBB0_210
	s_sleep 2
	s_add_i32 s11, s11, 1
	s_cmp_lt_u32 s11, 0x40000
	s_cbranch_scc1 .Lmy_fb_1_spin
	s_branch .LBB0_210

; __device__ __forceinline__ unsigned xb_ld(unsigned* p)              { return __hip_atomic_load(p, __ATOMIC_RELAXED, __HIP_MEMORY_SCOPE_AGENT); }
; __device__ __forceinline__ unsigned xb_add(unsigned* p, unsigned v) { return __hip_atomic_fetch_add(p, v, __ATOMIC_RELAXED, __HIP_MEMORY_SCOPE_AGENT); }
; #define XB_SPIN(cond, bar) do { unsigned _sp = 0; while (cond) { __builtin_amdgcn_s_sleep(1); \
;     if ((++_sp & 255u) == 0u) { if (xb_ld(&(bar)[XB_TMO])) break; if (_sp > XB_SPIN_CAP) { atomicAdd(&(bar)[XB_TMO], 1u); break; } } } } while (0)
; __device__ __forceinline__ void xcd_barrier(const XcdBarrier& b) {
;     asm volatile("s_waitcnt vmcnt(0)" ::: "memory");
;     __syncthreads();
;     if (threadIdx.x == 0) {
;         unsigned* bar = b.bar;
;         __builtin_amdgcn_s_waitcnt(0);
;         unsigned nloc = b.st[0], nx = b.st[1];
;         if (nloc == 0u) { xcd_barrier_complete(bar, b.x, nloc, nx); b.st[0] = nloc; b.st[1] = nx; }
;         const unsigned old = xb_add(&bar[XB_XSUB(b.x)], 1u);
;         const unsigned gen = old / nloc;
;         if (old + 1u == (gen + 1u) * nloc) {
;             __builtin_amdgcn_fence(__ATOMIC_RELEASE, "agent");
;             asm volatile("s_waitcnt vmcnt(0)" ::: "memory");
;             const unsigned og = xb_add(&bar[XB_TOP], 1u);
;             const unsigned tg = og / nx;
;             if (og + 1u == (tg + 1u) * nx) xb_add(&bar[XB_TOPGEN], 1u);
;             else XB_SPIN(xb_ld(&bar[XB_TOPGEN]) == tg, bar);
;             __builtin_amdgcn_fence(__ATOMIC_ACQUIRE, "agent");
;             xb_add(&bar[XB_XGEN(b.x)], 1u);
;             asm volatile("s_waitcnt vmcnt(0)" ::: "memory");
;         } else {
;             XB_SPIN(xb_ld(&bar[XB_XGEN(b.x)]) == gen, bar);
;             __builtin_amdgcn_fence(__ATOMIC_ACQUIRE, "agent");
;             asm volatile("s_waitcnt vmcnt(0)" ::: "memory");
;         }
.LBB0_723:
	s_cmp_gt_i32 s75, 3
	s_cselect_b64 s[0:1], -1, 0
	s_and_b64 s[2:3], s[2:3], s[0:1]
	s_andn2_b64 vcc, exec, s[2:3]
	s_cbranch_vccnz .LBB0_777
	s_waitcnt vmcnt(0)
	s_waitcnt vmcnt(0) lgkmcnt(0)
	s_barrier
	s_mov_b64 s[2:3], exec
	v_readlane_b32 s4, v254, 9
	v_readlane_b32 s5, v254, 10
	s_and_b64 s[4:5], s[2:3], s[4:5]
	s_mov_b64 exec, s[4:5]
	s_cbranch_execz .LBB0_776
	s_cmp_eq_u32 s74, 2
	s_cbranch_scc1 .Lmy_fb_2_orig
	s_add_i32 s4, 0, 0x26700
	v_mov_b32_e32 v0, s4
	ds_read2_b32 v[2:3], v0 offset1:1
	s_lshl_b32 s4, s88, 8
	s_add_u32 s4, s72, s4
	s_addc_u32 s5, s73, 0
	v_mov_b32_e32 v4, 0x1000
	v_mov_b32_e32 v5, 1
	global_atomic_add v4, v4, v5, s[4:5] offset:1024 sc0
	s_sub_i32 s6, 3, s74
	s_waitcnt lgkmcnt(0)
	v_readfirstlane_b32 s7, v2
	v_readfirstlane_b32 s8, v3
	s_mul_i32 s7, s7, s6
	s_add_i32 s6, s6, -1
	s_mul_i32 s8, s8, s6
	s_add_i32 s8, s8, 1
	v_mov_b32_e32 v6, 0x2000
	s_waitcnt vmcnt(0)
	v_readfirstlane_b32 s10, v4
	s_add_i32 s10, s10, 1
	s_cmp_lg_u32 s10, s7
	s_cbranch_scc1 .Lmy_fb_2_wait
	buffer_wbl2 sc1
	s_mov_b64 s[10:11], exec
	s_mov_b64 exec, 0xffff
	v_mbcnt_lo_u32_b32 v7, -1, 0
	v_lshlrev_b32_e32 v7, 8, v7
	v_add_u32_e32 v7, 0x2400, v7
	v_mov_b32_e32 v8, 1
	s_waitcnt vmcnt(0)
	global_atomic_add v7, v8, s[72:73]
	s_mov_b64 exec, s[10:11]

; __device__ __forceinline__ unsigned xb_ld(unsigned* p)              { return __hip_atomic_load(p, __ATOMIC_RELAXED, __HIP_MEMORY_SCOPE_AGENT); }
; __device__ __forceinline__ unsigned xb_add(unsigned* p, unsigned v) { return __hip_atomic_fetch_add(p, v, __ATOMIC_RELAXED, __HIP_MEMORY_SCOPE_AGENT); }
; #define XB_SPIN(cond, bar) do { unsigned _sp = 0; while (cond) { __builtin_amdgcn_s_sleep(1); \
;     if ((++_sp & 255u) == 0u) { if (xb_ld(&(bar)[XB_TMO])) break; if (_sp > XB_SPIN_CAP) { atomicAdd(&(bar)[XB_TMO], 1u); break; } } } } while (0)
; __device__ __forceinline__ void xcd_barrier(const XcdBarrier& b) {
;     asm volatile("s_waitcnt vmcnt(0)" ::: "memory");
;     __syncthreads();
;     if (threadIdx.x == 0) {
;         unsigned* bar = b.bar;
;         __builtin_amdgcn_s_waitcnt(0);
;         unsigned nloc = b.st[0], nx = b.st[1];
;         if (nloc == 0u) { xcd_barrier_complete(bar, b.x, nloc, nx); b.st[0] = nloc; b.st[1] = nx; }
;         const unsigned old = xb_add(&bar[XB_XSUB(b.x)], 1u);
;         const unsigned gen = old / nloc;
;         if (old + 1u == (gen + 1u) * nloc) {
;             __builtin_amdgcn_fence(__ATOMIC_RELEASE, "agent");
;             asm volatile("s_waitcnt vmcnt(0)" ::: "memory");
;             const unsigned og = xb_add(&bar[XB_TOP], 1u);
;             const unsigned tg = og / nx;
;             if (og + 1u == (tg + 1u) * nx) xb_add(&bar[XB_TOPGEN], 1u);
;             else XB_SPIN(xb_ld(&bar[XB_TOPGEN]) == tg, bar);
;             __builtin_amdgcn_fence(__ATOMIC_ACQUIRE, "agent");
;             xb_add(&bar[XB_XGEN(b.x)], 1u);
;             asm volatile("s_waitcnt vmcnt(0)" ::: "memory");
;         } else {
;             XB_SPIN(xb_ld(&bar[XB_XGEN(b.x)]) == gen, bar);
;             __builtin_amdgcn_fence(__ATOMIC_ACQUIRE, "agent");
;             asm volatile("s_waitcnt vmcnt(0)" ::: "memory");
;         }
.LBB0_808:
	s_cmp_gt_i32 s75, 4
	s_cselect_b64 s[2:3], -1, 0
	s_and_b64 s[0:1], s[0:1], s[2:3]
	s_andn2_b64 vcc, exec, s[0:1]
	s_cbranch_vccnz .LBB0_862
	s_waitcnt vmcnt(0)
	s_waitcnt vmcnt(0) lgkmcnt(0)
	s_barrier
	s_mov_b64 s[0:1], exec
	v_readlane_b32 s4, v254, 9
	v_readlane_b32 s5, v254, 10
	s_and_b64 s[4:5], s[0:1], s[4:5]
	s_mov_b64 exec, s[4:5]
	s_cbranch_execz .LBB0_861
	s_cmp_eq_u32 s74, 3
	s_cbranch_scc1 .Lmy_fb_3_orig
	s_add_i32 s4, 0, 0x26700
	v_mov_b32_e32 v0, s4
	ds_read2_b32 v[2:3], v0 offset1:1
	s_lshl_b32 s4, s88, 8
	s_add_u32 s4, s72, s4
	s_addc_u32 s5, s73, 0
	v_mov_b32_e32 v4, 0x1000
	v_mov_b32_e32 v5, 1
	global_atomic_add v4, v4, v5, s[4:5] offset:1024 sc0
	s_sub_i32 s6, 4, s74
	s_waitcnt lgkmcnt(0)
	v_readfirstlane_b32 s7, v2
	v_readfirstlane_b32 s8, v3
	s_mul_i32 s7, s7, s6
	s_add_i32 s6, s6, -1
	s_mul_i32 s8, s8, s6
	s_add_i32 s8, s8, 1
	v_mov_b32_e32 v6, 0x2000
	s_waitcnt vmcnt(0)
	v_readfirstlane_b32 s10, v4
	s_add_i32 s10, s10, 1
	s_cmp_lg_u32 s10, s7
	s_cbranch_scc1 .Lmy_fb_3_wait
	buffer_wbl2 sc1
	s_mov_b64 s[10:11], exec
	s_mov_b64 exec, 0xffff
	v_mbcnt_lo_u32_b32 v7, -1, 0
	v_lshlrev_b32_e32 v7, 8, v7
	v_add_u32_e32 v7, 0x2400, v7
	v_mov_b32_e32 v8, 1
	s_waitcnt vmcnt(0)
	global_atomic_add v7, v8, s[72:73]
	s_mov_b64 exec, s[10:11]

; __device__ __forceinline__ unsigned xb_ld(unsigned* p)              { return __hip_atomic_load(p, __ATOMIC_RELAXED, __HIP_MEMORY_SCOPE_AGENT); }
; __device__ __forceinline__ unsigned xb_add(unsigned* p, unsigned v) { return __hip_atomic_fetch_add(p, v, __ATOMIC_RELAXED, __HIP_MEMORY_SCOPE_AGENT); }
; #define XB_SPIN(cond, bar) do { unsigned _sp = 0; while (cond) { __builtin_amdgcn_s_sleep(1); \
;     if ((++_sp & 255u) == 0u) { if (xb_ld(&(bar)[XB_TMO])) break; if (_sp > XB_SPIN_CAP) { atomicAdd(&(bar)[XB_TMO], 1u); break; } } } } while (0)
; __device__ __forceinline__ void xcd_barrier(const XcdBarrier& b) {
;     asm volatile("s_waitcnt vmcnt(0)" ::: "memory");
;     __syncthreads();
;     if (threadIdx.x == 0) {
;         unsigned* bar = b.bar;
;         __builtin_amdgcn_s_waitcnt(0);
;         unsigned nloc = b.st[0], nx = b.st[1];
;         if (nloc == 0u) { xcd_barrier_complete(bar, b.x, nloc, nx); b.st[0] = nloc; b.st[1] = nx; }
;         const unsigned old = xb_add(&bar[XB_XSUB(b.x)], 1u);
;         const unsigned gen = old / nloc;
;         if (old + 1u == (gen + 1u) * nloc) {
;             __builtin_amdgcn_fence(__ATOMIC_RELEASE, "agent");
;             asm volatile("s_waitcnt vmcnt(0)" ::: "memory");
;             const unsigned og = xb_add(&bar[XB_TOP], 1u);
;             const unsigned tg = og / nx;
;             if (og + 1u == (tg + 1u) * nx) xb_add(&bar[XB_TOPGEN], 1u);
;             else XB_SPIN(xb_ld(&bar[XB_TOPGEN]) == tg, bar);
;             __builtin_amdgcn_fence(__ATOMIC_ACQUIRE, "agent");
;             xb_add(&bar[XB_XGEN(b.x)], 1u);
;             asm volatile("s_waitcnt vmcnt(0)" ::: "memory");
;         } else {
;             XB_SPIN(xb_ld(&bar[XB_XGEN(b.x)]) == gen, bar);
;             __builtin_amdgcn_fence(__ATOMIC_ACQUIRE, "agent");
;             asm volatile("s_waitcnt vmcnt(0)" ::: "memory");
;         }
.LBB0_905:
	s_cmp_gt_i32 s75, 5
	s_cselect_b64 s[2:3], -1, 0
	s_and_b64 s[0:1], s[0:1], s[2:3]
	s_andn2_b64 vcc, exec, s[0:1]
	s_cbranch_vccnz .LBB0_959
	s_waitcnt vmcnt(0)
	s_waitcnt vmcnt(0) lgkmcnt(0)
	s_barrier
	s_mov_b64 s[0:1], exec
	v_readlane_b32 s4, v254, 9
	v_readlane_b32 s5, v254, 10
	s_and_b64 s[4:5], s[0:1], s[4:5]
	s_mov_b64 exec, s[4:5]
	s_cbranch_execz .LBB0_958
	s_cmp_eq_u32 s74, 4
	s_cbranch_scc1 .Lmy_fb_4_orig
	s_add_i32 s4, 0, 0x26700
	v_mov_b32_e32 v0, s4
	ds_read2_b32 v[2:3], v0 offset1:1
	s_lshl_b32 s4, s88, 8
	s_add_u32 s4, s72, s4
	s_addc_u32 s5, s73, 0
	v_mov_b32_e32 v4, 0x1000
	v_mov_b32_e32 v5, 1
	global_atomic_add v4, v4, v5, s[4:5] offset:1024 sc0
	s_sub_i32 s6, 5, s74
	s_waitcnt lgkmcnt(0)
	v_readfirstlane_b32 s7, v2
	v_readfirstlane_b32 s8, v3
	s_mul_i32 s7, s7, s6
	s_add_i32 s6, s6, -1
	s_mul_i32 s8, s8, s6
	s_add_i32 s8, s8, 1
	v_mov_b32_e32 v6, 0x2000
	s_waitcnt vmcnt(0)
	v_readfirstlane_b32 s10, v4
	s_add_i32 s10, s10, 1
	s_cmp_lg_u32 s10, s7
	s_cbranch_scc1 .Lmy_fb_4_wait
	buffer_wbl2 sc1
	s_mov_b64 s[10:11], exec
	s_mov_b64 exec, 0xffff
	v_mbcnt_lo_u32_b32 v7, -1, 0
	v_lshlrev_b32_e32 v7, 8, v7
	v_add_u32_e32 v7, 0x2400, v7
	v_mov_b32_e32 v8, 1
	s_waitcnt vmcnt(0)
	global_atomic_add v7, v8, s[72:73]
	s_mov_b64 exec, s[10:11]

; __device__ __forceinline__ unsigned xb_ld(unsigned* p)              { return __hip_atomic_load(p, __ATOMIC_RELAXED, __HIP_MEMORY_SCOPE_AGENT); }
; __device__ __forceinline__ unsigned xb_add(unsigned* p, unsigned v) { return __hip_atomic_fetch_add(p, v, __ATOMIC_RELAXED, __HIP_MEMORY_SCOPE_AGENT); }
; #define XB_SPIN(cond, bar) do { unsigned _sp = 0; while (cond) { __builtin_amdgcn_s_sleep(1); \
;     if ((++_sp & 255u) == 0u) { if (xb_ld(&(bar)[XB_TMO])) break; if (_sp > XB_SPIN_CAP) { atomicAdd(&(bar)[XB_TMO], 1u); break; } } } } while (0)
; __device__ __forceinline__ void xcd_barrier(const XcdBarrier& b) {
;     asm volatile("s_waitcnt vmcnt(0)" ::: "memory");
;     __syncthreads();
;     if (threadIdx.x == 0) {
;         unsigned* bar = b.bar;
;         __builtin_amdgcn_s_waitcnt(0);
;         unsigned nloc = b.st[0], nx = b.st[1];
;         if (nloc == 0u) { xcd_barrier_complete(bar, b.x, nloc, nx); b.st[0] = nloc; b.st[1] = nx; }
;         const unsigned old = xb_add(&bar[XB_XSUB(b.x)], 1u);
;         const unsigned gen = old / nloc;
;         if (old + 1u == (gen + 1u) * nloc) {
;             __builtin_amdgcn_fence(__ATOMIC_RELEASE, "agent");
;             asm volatile("s_waitcnt vmcnt(0)" ::: "memory");
;             const unsigned og = xb_add(&bar[XB_TOP], 1u);
;             const unsigned tg = og / nx;
;             if (og + 1u == (tg + 1u) * nx) xb_add(&bar[XB_TOPGEN], 1u);
;             else XB_SPIN(xb_ld(&bar[XB_TOPGEN]) == tg, bar);
;             __builtin_amdgcn_fence(__ATOMIC_ACQUIRE, "agent");
;             xb_add(&bar[XB_XGEN(b.x)], 1u);
;             asm volatile("s_waitcnt vmcnt(0)" ::: "memory");
;         } else {
;             XB_SPIN(xb_ld(&bar[XB_XGEN(b.x)]) == gen, bar);
;             __builtin_amdgcn_fence(__ATOMIC_ACQUIRE, "agent");
;             asm volatile("s_waitcnt vmcnt(0)" ::: "memory");
;         }
.LBB0_976:
	s_cmp_gt_i32 s75, 6
	s_cselect_b64 s[2:3], -1, 0
	s_and_b64 s[0:1], s[0:1], s[2:3]
	s_andn2_b64 vcc, exec, s[0:1]
	s_cbranch_vccnz .LBB0_1030
	s_waitcnt vmcnt(0)
	s_waitcnt vmcnt(0) lgkmcnt(0)
	s_barrier
	s_mov_b64 s[0:1], exec
	v_readlane_b32 s4, v254, 9
	v_readlane_b32 s5, v254, 10
	s_and_b64 s[4:5], s[0:1], s[4:5]
	s_mov_b64 exec, s[4:5]
	s_cbranch_execz .LBB0_1029
	s_cmp_eq_u32 s74, 5
	s_cbranch_scc1 .Lmy_fb_5_orig
	s_add_i32 s4, 0, 0x26700
	v_mov_b32_e32 v0, s4
	ds_read2_b32 v[2:3], v0 offset1:1
	s_lshl_b32 s4, s88, 8
	s_add_u32 s4, s72, s4
	s_addc_u32 s5, s73, 0
	v_mov_b32_e32 v4, 0x1000
	v_mov_b32_e32 v5, 1
	global_atomic_add v4, v4, v5, s[4:5] offset:1024 sc0
	s_sub_i32 s6, 6, s74
	s_waitcnt lgkmcnt(0)
	v_readfirstlane_b32 s7, v2
	v_readfirstlane_b32 s8, v3
	s_mul_i32 s7, s7, s6
	s_add_i32 s6, s6, -1
	s_mul_i32 s8, s8, s6
	s_add_i32 s8, s8, 1
	v_mov_b32_e32 v6, 0x2000
	s_waitcnt vmcnt(0)
	v_readfirstlane_b32 s10, v4
	s_add_i32 s10, s10, 1
	s_cmp_lg_u32 s10, s7
	s_cbranch_scc1 .Lmy_fb_5_wait
	buffer_wbl2 sc1
	s_mov_b64 s[10:11], exec
	s_mov_b64 exec, 0xffff
	v_mbcnt_lo_u32_b32 v7, -1, 0
	v_lshlrev_b32_e32 v7, 8, v7
	v_add_u32_e32 v7, 0x2400, v7
	v_mov_b32_e32 v8, 1
	s_waitcnt vmcnt(0)
	global_atomic_add v7, v8, s[72:73]
	s_mov_b64 exec, s[10:11]
